# hybrid in-proj and RWKV r/k/v GEMM epilogues: plain bf16 tiles take a fast path with v_permlane16_swap + 16-byte stores (32 -> 16 stores per tile)
# speedup vs baseline: 1.0276x; 1.0086x over previous
;     ...
;       for (int kt = 0; kt < KT; kt++) {
;         {
;           const bf16_t* apx = ap;
;           int kc = kt * 64;
;           if (SHIFT && kc >= 1024) { apx = ap - lda; kc -= 1024; }
; #pragma unroll
;           for (int i = 0; i < 8; i++)
;             __builtin_amdgcn_global_load_lds((const unsigned*)(apx + i * a32 + kc), sbase + i * 1024, 16, 0, 0);
; #pragma unroll
;           for (int i = 0; i < 4; i++)
;             __builtin_amdgcn_global_load_lds((const unsigned*)(bp + i * b32 + kt * 64), sbase + 8192 + i * 1024, 16, 0, 0);
;         }
;         asm volatile("s_waitcnt vmcnt(0)" ::: "memory");
;         __syncthreads();
; #pragma unroll
;         for (int kk = 0; kk < 2; kk++) {
;           bf16x8 af[MI], bfr[4];
;           const int csw = (((kk * 4 + fq) ^ fsw) << 3);
; #pragma unroll
;           for (int mi = 0; mi < MI; mi++) af[mi] = *(const bf16x8*)(smem + (wm * 128 + mi * 16 + fr) * 64 + csw);
; #pragma unroll
;           for (int ni = 0; ni < 4; ni++) bfr[ni] = *(const bf16x8*)(smem + 16384 + (wn * 64 + ni * 16 + fr) * 64 + csw);
; #pragma unroll
;           for (int mi = 0; mi < MI; mi++)
; #pragma unroll
;             for (int ni = 0; ni < 4; ni++)
;               acc[mi][ni] = __builtin_amdgcn_mfma_f32_16x16x32_bf16(bfr[ni], af[mi], acc[mi][ni], 0, 0, 0);
;         }
;         __syncthreads();
;       }
.LBB0_618:
	s_cmp_gt_u32 s6, 15
	s_cselect_b64 s[10:11], -1, 0
	s_add_i32 s7, s5, 0xfffffc00
	s_and_b64 s[10:11], s[10:11], exec
	s_cselect_b32 s11, -1, 0
	s_cselect_b32 s10, 0xfffff800, 0
	v_lshl_add_u64 v[138:139], v[170:171], 0, s[10:11]
	s_cselect_b32 s10, s7, s5
	s_ashr_i32 s11, s10, 31
	v_lshl_add_u64 v[138:139], s[10:11], 1, v[138:139]
	v_readfirstlane_b32 s7, v174
	v_add_u32_e32 v8, 0x1000, v174
	v_lshl_add_u64 v[140:141], v[138:139], 0, s[16:17]
	s_mov_b32 m0, s7
	v_readfirstlane_b32 s7, v8
	v_add_u32_e32 v8, 0x2000, v174
	global_load_lds_dwordx4 v[140:141], off
	v_lshl_add_u64 v[140:141], v[138:139], 0, s[18:19]
	s_mov_b32 m0, s7
	v_readfirstlane_b32 s7, v8
	v_add_u32_e32 v8, 0x3000, v174
	global_load_lds_dwordx4 v[140:141], off
	v_lshl_add_u64 v[140:141], v[138:139], 0, s[20:21]
	s_mov_b32 m0, s7
	v_readfirstlane_b32 s7, v8
	v_add_u32_e32 v8, 0x4000, v174
	global_load_lds_dwordx4 v[140:141], off
	v_lshl_add_u64 v[140:141], v[138:139], 0, s[22:23]
	s_mov_b32 m0, s7
	v_readfirstlane_b32 s7, v8
	v_add_u32_e32 v8, 0x5000, v174
	global_load_lds_dwordx4 v[140:141], off
	v_lshl_add_u64 v[140:141], v[138:139], 0, s[24:25]
	s_mov_b32 m0, s7
	v_readfirstlane_b32 s7, v8
	v_add_u32_e32 v8, 0x6000, v174
	global_load_lds_dwordx4 v[140:141], off
	v_lshl_add_u64 v[140:141], v[138:139], 0, s[26:27]
	s_mov_b32 m0, s7
	v_readfirstlane_b32 s7, v8
	v_add_u32_e32 v8, 0x7000, v174
	global_load_lds_dwordx4 v[140:141], off
	v_lshl_add_u64 v[140:141], v[138:139], 0, s[14:15]
	s_mov_b32 m0, s7
	v_readfirstlane_b32 s7, v8
	global_load_lds_dwordx4 v[140:141], off
	v_lshl_add_u64 v[138:139], v[138:139], 0, s[28:29]
	s_mov_b32 m0, s7
	v_add_u32_e32 v8, 0x8000, v174
	global_load_lds_dwordx4 v[138:139], off
	v_lshl_add_u64 v[138:139], v[172:173], 0, s[0:1]
	s_mov_b64 s[10:11], 0x6180000
	v_readfirstlane_b32 s7, v8
	v_add_u32_e32 v8, 0x9000, v174
	v_lshl_add_u64 v[140:141], v[138:139], 0, s[10:11]
	s_mov_b32 m0, s7
	s_mov_b64 s[10:11], 0x61a0000
	v_readfirstlane_b32 s7, v8
	v_add_u32_e32 v8, 0xa000, v174
	global_load_lds_dwordx4 v[140:141], off
	v_lshl_add_u64 v[140:141], v[138:139], 0, s[10:11]
	s_mov_b32 m0, s7
	s_mov_b64 s[10:11], 0x61c0000
	v_readfirstlane_b32 s7, v8
	v_add_u32_e32 v8, 0xb000, v174
	global_load_lds_dwordx4 v[140:141], off
	v_lshl_add_u64 v[140:141], v[138:139], 0, s[10:11]
	s_mov_b32 m0, s7
	s_mov_b64 s[10:11], 0x61e0000
	v_readfirstlane_b32 s7, v8
	global_load_lds_dwordx4 v[140:141], off
	v_lshl_add_u64 v[138:139], v[138:139], 0, s[10:11]
	s_mov_b32 m0, s7
	v_add_u32_e32 v8, v177, v178
	global_load_lds_dwordx4 v[138:139], off
	s_waitcnt vmcnt(0)
	s_waitcnt vmcnt(0) lgkmcnt(0)
	s_barrier
	ds_read_b128 v[182:185], v8
	ds_read_b128 v[186:189], v8 offset:2048
	ds_read_b128 v[158:161], v8 offset:4096
	ds_read_b128 v[154:157], v8 offset:6144
	ds_read_b128 v[150:153], v8 offset:8192
	ds_read_b128 v[146:149], v8 offset:10240
	ds_read_b128 v[142:145], v8 offset:12288
	ds_read_b128 v[138:141], v8 offset:14336
	ds_read_b128 v[190:193], v180 offset:32768
	ds_read_b128 v[194:197], v180 offset:34816
	ds_read_b128 v[198:201], v180 offset:36864
	ds_read_b128 v[202:205], v180 offset:38912
	v_add_u32_e32 v8, v179, v178
	s_waitcnt lgkmcnt(3)
	v_mfma_f32_16x16x32_bf16 v[134:137], v[190:193], v[182:185], v[134:137]
	s_add_i32 s6, s6, 1
	s_add_u32 s0, s0, 0x80
	s_addc_u32 s1, s1, 0
	s_waitcnt lgkmcnt(2)
	v_mfma_f32_16x16x32_bf16 v[130:133], v[194:197], v[182:185], v[130:133]
	s_add_i32 s5, s5, 64
	s_cmpk_eq_i32 s0, 0x1000
	s_waitcnt lgkmcnt(1)
	v_mfma_f32_16x16x32_bf16 v[126:129], v[198:201], v[182:185], v[126:129]
	s_waitcnt lgkmcnt(0)
	v_mfma_f32_16x16x32_bf16 v[122:125], v[202:205], v[182:185], v[122:125]
	v_mfma_f32_16x16x32_bf16 v[118:121], v[190:193], v[186:189], v[118:121]
	v_mfma_f32_16x16x32_bf16 v[114:117], v[194:197], v[186:189], v[114:117]
	v_mfma_f32_16x16x32_bf16 v[110:113], v[198:201], v[186:189], v[110:113]
	v_mfma_f32_16x16x32_bf16 v[106:109], v[202:205], v[186:189], v[106:109]
	v_mfma_f32_16x16x32_bf16 v[102:105], v[190:193], v[158:161], v[102:105]
	v_mfma_f32_16x16x32_bf16 v[98:101], v[194:197], v[158:161], v[98:101]
	v_mfma_f32_16x16x32_bf16 v[94:97], v[198:201], v[158:161], v[94:97]
	v_mfma_f32_16x16x32_bf16 v[90:93], v[202:205], v[158:161], v[90:93]
	v_mfma_f32_16x16x32_bf16 v[86:89], v[190:193], v[154:157], v[86:89]
	v_mfma_f32_16x16x32_bf16 v[82:85], v[194:197], v[154:157], v[82:85]
	v_mfma_f32_16x16x32_bf16 v[78:81], v[198:201], v[154:157], v[78:81]
	v_mfma_f32_16x16x32_bf16 v[74:77], v[202:205], v[154:157], v[74:77]
	v_mfma_f32_16x16x32_bf16 v[70:73], v[190:193], v[150:153], v[70:73]
	v_mfma_f32_16x16x32_bf16 v[66:69], v[194:197], v[150:153], v[66:69]
	v_mfma_f32_16x16x32_bf16 v[62:65], v[198:201], v[150:153], v[62:65]
	v_mfma_f32_16x16x32_bf16 v[58:61], v[202:205], v[150:153], v[58:61]
	v_mfma_f32_16x16x32_bf16 v[54:57], v[190:193], v[146:149], v[54:57]
	v_mfma_f32_16x16x32_bf16 v[50:53], v[194:197], v[146:149], v[50:53]
	v_mfma_f32_16x16x32_bf16 v[46:49], v[198:201], v[146:149], v[46:49]
	v_mfma_f32_16x16x32_bf16 v[42:45], v[202:205], v[146:149], v[42:45]
	v_mfma_f32_16x16x32_bf16 v[38:41], v[190:193], v[142:145], v[38:41]
	v_mfma_f32_16x16x32_bf16 v[34:37], v[194:197], v[142:145], v[34:37]
	v_mfma_f32_16x16x32_bf16 v[30:33], v[198:201], v[142:145], v[30:33]
	v_mfma_f32_16x16x32_bf16 v[26:29], v[202:205], v[142:145], v[26:29]
	v_mfma_f32_16x16x32_bf16 v[22:25], v[190:193], v[138:141], v[22:25]
	v_mfma_f32_16x16x32_bf16 v[18:21], v[194:197], v[138:141], v[18:21]
	v_mfma_f32_16x16x32_bf16 v[14:17], v[198:201], v[138:141], v[14:17]
	v_mfma_f32_16x16x32_bf16 v[10:13], v[202:205], v[138:141], v[10:13]
	ds_read_b128 v[138:141], v8
	ds_read_b128 v[142:145], v8 offset:2048
	ds_read_b128 v[146:149], v8 offset:4096
	ds_read_b128 v[150:153], v8 offset:6144
	ds_read_b128 v[154:157], v8 offset:8192
	ds_read_b128 v[158:161], v8 offset:10240
	ds_read_b128 v[182:185], v8 offset:12288
	ds_read_b128 v[186:189], v8 offset:14336
	ds_read_b128 v[190:193], v181 offset:32768
	ds_read_b128 v[194:197], v181 offset:34816
	ds_read_b128 v[198:201], v181 offset:36864
	ds_read_b128 v[202:205], v181 offset:38912
	s_waitcnt lgkmcnt(0)
	s_barrier
;     ...
;           for (int mi = 0; mi < MI; mi++)
; #pragma unroll
;             for (int ni = 0; ni < 4; ni++)
;               acc[mi][ni] = __builtin_amdgcn_mfma_f32_16x16x32_bf16(bfr[ni], af[mi], acc[mi][ni], 0, 0, 0);
;         }
;         __syncthreads();
;     ...
;             } else if constexpr (EPI == EPI_RK1) {
;               uint2 o;
;               if (col < 3072) {
;                 o.x = pack2(a[0], a[1]); o.y = pack2(a[2], a[3]);
;                 *(uint2*)(e.b0 + (row * (unsigned)RKLD + col)) = o;
;               } else if (col < 3392) {
	v_mfma_f32_16x16x32_bf16 v[134:137], v[190:193], v[138:141], v[134:137]
	v_mfma_f32_16x16x32_bf16 v[130:133], v[194:197], v[138:141], v[130:133]
	v_mfma_f32_16x16x32_bf16 v[126:129], v[198:201], v[138:141], v[126:129]
	v_mfma_f32_16x16x32_bf16 v[122:125], v[202:205], v[138:141], v[122:125]
	v_mfma_f32_16x16x32_bf16 v[118:121], v[190:193], v[142:145], v[118:121]
	v_mfma_f32_16x16x32_bf16 v[114:117], v[194:197], v[142:145], v[114:117]
	v_mfma_f32_16x16x32_bf16 v[110:113], v[198:201], v[142:145], v[110:113]
	v_mfma_f32_16x16x32_bf16 v[106:109], v[202:205], v[142:145], v[106:109]
	v_mfma_f32_16x16x32_bf16 v[102:105], v[190:193], v[146:149], v[102:105]
	v_mfma_f32_16x16x32_bf16 v[98:101], v[194:197], v[146:149], v[98:101]
	v_mfma_f32_16x16x32_bf16 v[94:97], v[198:201], v[146:149], v[94:97]
	v_mfma_f32_16x16x32_bf16 v[90:93], v[202:205], v[146:149], v[90:93]
	v_mfma_f32_16x16x32_bf16 v[86:89], v[190:193], v[150:153], v[86:89]
	v_mfma_f32_16x16x32_bf16 v[82:85], v[194:197], v[150:153], v[82:85]
	v_mfma_f32_16x16x32_bf16 v[78:81], v[198:201], v[150:153], v[78:81]
	v_mfma_f32_16x16x32_bf16 v[74:77], v[202:205], v[150:153], v[74:77]
	v_mfma_f32_16x16x32_bf16 v[70:73], v[190:193], v[154:157], v[70:73]
	v_mfma_f32_16x16x32_bf16 v[66:69], v[194:197], v[154:157], v[66:69]
	v_mfma_f32_16x16x32_bf16 v[62:65], v[198:201], v[154:157], v[62:65]
	v_mfma_f32_16x16x32_bf16 v[58:61], v[202:205], v[154:157], v[58:61]
	v_mfma_f32_16x16x32_bf16 v[54:57], v[190:193], v[158:161], v[54:57]
	v_mfma_f32_16x16x32_bf16 v[50:53], v[194:197], v[158:161], v[50:53]
	v_mfma_f32_16x16x32_bf16 v[46:49], v[198:201], v[158:161], v[46:49]
	v_mfma_f32_16x16x32_bf16 v[42:45], v[202:205], v[158:161], v[42:45]
	v_mfma_f32_16x16x32_bf16 v[38:41], v[190:193], v[182:185], v[38:41]
	v_mfma_f32_16x16x32_bf16 v[34:37], v[194:197], v[182:185], v[34:37]
	v_mfma_f32_16x16x32_bf16 v[30:33], v[198:201], v[182:185], v[30:33]
	v_mfma_f32_16x16x32_bf16 v[26:29], v[202:205], v[182:185], v[26:29]
	v_mfma_f32_16x16x32_bf16 v[22:25], v[190:193], v[186:189], v[22:25]
	v_mfma_f32_16x16x32_bf16 v[18:21], v[194:197], v[186:189], v[18:21]
	v_mfma_f32_16x16x32_bf16 v[14:17], v[198:201], v[186:189], v[14:17]
	v_mfma_f32_16x16x32_bf16 v[10:13], v[202:205], v[186:189], v[10:13]
	s_cbranch_scc0 .LBB0_618
	v_add_u32_e32 v142, s4, v176
	s_movk_i32 s0, 0x140
	s_cmpk_gt_u32 s13, 0xbff
	v_or_b32_e32 v140, s13, v175
	v_mul_lo_u32 v8, v142, s0
	s_cselect_b64 s[4:5], -1, 0
	s_movk_i32 s0, 0xd40
	v_add_u32_e32 v141, 0xfffff400, v8
	s_mov_b64 s[6:7], -1
	s_and_b64 vcc, exec, s[4:5]
	v_cmp_gt_u32_e64 s[0:1], s0, v140
	s_mov_b32 s28, s30
	s_mov_b64 s[26:27], s[48:49]
	s_cbranch_vccnz .Lrk_slow
; __device__ __forceinline__ float sigmoidf_(float x) { return __builtin_amdgcn_rcpf(1.f + __expf(-x)); }
;     ...
;             } else if constexpr (EPI == EPI_RK1) {
;               uint2 o;
;               if (col < 3072) {
;                 o.x = pack2(a[0], a[1]); o.y = pack2(a[2], a[3]);
;                 *(uint2*)(e.b0 + (row * (unsigned)RKLD + col)) = o;
;               } else if (col < 3392) {
;                 if (col < 3136) { o.x = pack2(tanhf(a[0]), tanhf(a[1])); o.y = pack2(tanhf(a[2]), tanhf(a[3])); }
;                 else if (col < 3200) { o.x = pack2(a[0], a[1]); o.y = pack2(a[2], a[3]); }
;                 else if (col < 3360) { o.x = pack2(sigmoidf_(a[0]), sigmoidf_(a[1])); o.y = pack2(sigmoidf_(a[2]), sigmoidf_(a[3])); }
;                 else { o.x = 0u; o.y = 0u; }
;                 *(uint2*)(e.b1 + (row * (unsigned)MIDLD + (col - 3072))) = o;
;               }
	s_movk_i32 s0, 0xc00
	v_mul_lo_u32 v138, v142, s0
	v_bfe_u32 v139, v2, 4, 1
	v_add_u32_e32 v138, v138, v140
	v_mul_u32_u24_e32 v139, 12, v139
	s_nop 0
	v_add_u32_e32 v138, v138, v139
	v_cvt_pk_bf16_f32 v190, v134, v135
	v_cvt_pk_bf16_f32 v191, v136, v137
	v_cvt_pk_bf16_f32 v192, v130, v131
	v_cvt_pk_bf16_f32 v193, v132, v133
	v_mov_b32_e32 v8, v138
	v_lshl_add_u64 v[202:203], v[8:9], 1, s[52:53]
	v_permlane16_swap_b32 v190, v192
	v_permlane16_swap_b32 v191, v193
	s_nop 1
	global_store_dwordx4 v[202:203], v[190:193], off
	v_cvt_pk_bf16_f32 v194, v126, v127
	v_cvt_pk_bf16_f32 v195, v128, v129
	v_cvt_pk_bf16_f32 v196, v122, v123
	v_cvt_pk_bf16_f32 v197, v124, v125
	v_add_u32_e32 v8, 0x20, v138
	v_lshl_add_u64 v[204:205], v[8:9], 1, s[52:53]
	v_permlane16_swap_b32 v194, v196
	v_permlane16_swap_b32 v195, v197
	s_nop 1
	global_store_dwordx4 v[204:205], v[194:197], off
	v_cvt_pk_bf16_f32 v198, v118, v119
	v_cvt_pk_bf16_f32 v199, v120, v121
	v_cvt_pk_bf16_f32 v200, v114, v115
	v_cvt_pk_bf16_f32 v201, v116, v117
	v_add_u32_e32 v8, 0xc000, v138
	v_lshl_add_u64 v[144:145], v[8:9], 1, s[52:53]
	v_permlane16_swap_b32 v198, v200
	v_permlane16_swap_b32 v199, v201
	s_nop 1
	global_store_dwordx4 v[144:145], v[198:201], off
	v_cvt_pk_bf16_f32 v190, v110, v111
	v_cvt_pk_bf16_f32 v191, v112, v113
	v_cvt_pk_bf16_f32 v192, v106, v107
	v_cvt_pk_bf16_f32 v193, v108, v109
	v_add_u32_e32 v8, 0xc020, v138
	v_lshl_add_u64 v[202:203], v[8:9], 1, s[52:53]
	v_permlane16_swap_b32 v190, v192
	v_permlane16_swap_b32 v191, v193
	s_nop 1
	global_store_dwordx4 v[202:203], v[190:193], off
	v_cvt_pk_bf16_f32 v194, v102, v103
	v_cvt_pk_bf16_f32 v195, v104, v105
	v_cvt_pk_bf16_f32 v196, v98, v99
	v_cvt_pk_bf16_f32 v197, v100, v101
	v_add_u32_e32 v8, 0x18000, v138
	v_lshl_add_u64 v[204:205], v[8:9], 1, s[52:53]
	v_permlane16_swap_b32 v194, v196
	v_permlane16_swap_b32 v195, v197
	s_nop 1
	global_store_dwordx4 v[204:205], v[194:197], off
	v_cvt_pk_bf16_f32 v198, v94, v95
	v_cvt_pk_bf16_f32 v199, v96, v97
	v_cvt_pk_bf16_f32 v200, v90, v91
	v_cvt_pk_bf16_f32 v201, v92, v93
	v_add_u32_e32 v8, 0x18020, v138
	v_lshl_add_u64 v[144:145], v[8:9], 1, s[52:53]
	v_permlane16_swap_b32 v198, v200
	v_permlane16_swap_b32 v199, v201
	s_nop 1
	global_store_dwordx4 v[144:145], v[198:201], off
	v_cvt_pk_bf16_f32 v190, v86, v87
	v_cvt_pk_bf16_f32 v191, v88, v89
	v_cvt_pk_bf16_f32 v192, v82, v83
	v_cvt_pk_bf16_f32 v193, v84, v85
	v_add_u32_e32 v8, 0x24000, v138
	v_lshl_add_u64 v[202:203], v[8:9], 1, s[52:53]
	v_permlane16_swap_b32 v190, v192
	v_permlane16_swap_b32 v191, v193
	s_nop 1
	global_store_dwordx4 v[202:203], v[190:193], off
	v_cvt_pk_bf16_f32 v194, v78, v79
	v_cvt_pk_bf16_f32 v195, v80, v81
	v_cvt_pk_bf16_f32 v196, v74, v75
	v_cvt_pk_bf16_f32 v197, v76, v77
	v_add_u32_e32 v8, 0x24020, v138
	v_lshl_add_u64 v[204:205], v[8:9], 1, s[52:53]
	v_permlane16_swap_b32 v194, v196
	v_permlane16_swap_b32 v195, v197
	s_nop 1
	global_store_dwordx4 v[204:205], v[194:197], off
	v_cvt_pk_bf16_f32 v198, v70, v71
	v_cvt_pk_bf16_f32 v199, v72, v73
	v_cvt_pk_bf16_f32 v200, v66, v67
	v_cvt_pk_bf16_f32 v201, v68, v69
	v_add_u32_e32 v8, 0x30000, v138
	v_lshl_add_u64 v[144:145], v[8:9], 1, s[52:53]
	v_permlane16_swap_b32 v198, v200
	v_permlane16_swap_b32 v199, v201
	s_nop 1
	global_store_dwordx4 v[144:145], v[198:201], off
	v_cvt_pk_bf16_f32 v190, v62, v63
	v_cvt_pk_bf16_f32 v191, v64, v65
	v_cvt_pk_bf16_f32 v192, v58, v59
	v_cvt_pk_bf16_f32 v193, v60, v61
	v_add_u32_e32 v8, 0x30020, v138
	v_lshl_add_u64 v[202:203], v[8:9], 1, s[52:53]
	v_permlane16_swap_b32 v190, v192
	v_permlane16_swap_b32 v191, v193
	s_nop 1
	global_store_dwordx4 v[202:203], v[190:193], off
	v_cvt_pk_bf16_f32 v194, v54, v55
	v_cvt_pk_bf16_f32 v195, v56, v57
	v_cvt_pk_bf16_f32 v196, v50, v51
	v_cvt_pk_bf16_f32 v197, v52, v53
	v_add_u32_e32 v8, 0x3c000, v138
	v_lshl_add_u64 v[204:205], v[8:9], 1, s[52:53]
	v_permlane16_swap_b32 v194, v196
	v_permlane16_swap_b32 v195, v197
	s_nop 1
	global_store_dwordx4 v[204:205], v[194:197], off
	v_cvt_pk_bf16_f32 v198, v46, v47
	v_cvt_pk_bf16_f32 v199, v48, v49
	v_cvt_pk_bf16_f32 v200, v42, v43
	v_cvt_pk_bf16_f32 v201, v44, v45
	v_add_u32_e32 v8, 0x3c020, v138
	v_lshl_add_u64 v[144:145], v[8:9], 1, s[52:53]
	v_permlane16_swap_b32 v198, v200
	v_permlane16_swap_b32 v199, v201
	s_nop 1
	global_store_dwordx4 v[144:145], v[198:201], off
	v_cvt_pk_bf16_f32 v190, v38, v39
	v_cvt_pk_bf16_f32 v191, v40, v41
	v_cvt_pk_bf16_f32 v192, v34, v35
	v_cvt_pk_bf16_f32 v193, v36, v37
	v_add_u32_e32 v8, 0x48000, v138
	v_lshl_add_u64 v[202:203], v[8:9], 1, s[52:53]
	v_permlane16_swap_b32 v190, v192
	v_permlane16_swap_b32 v191, v193
	s_nop 1
	global_store_dwordx4 v[202:203], v[190:193], off
	v_cvt_pk_bf16_f32 v194, v30, v31
	v_cvt_pk_bf16_f32 v195, v32, v33
	v_cvt_pk_bf16_f32 v196, v26, v27
	v_cvt_pk_bf16_f32 v197, v28, v29
	v_add_u32_e32 v8, 0x48020, v138
	v_lshl_add_u64 v[204:205], v[8:9], 1, s[52:53]
	v_permlane16_swap_b32 v194, v196
	v_permlane16_swap_b32 v195, v197
	s_nop 1
	global_store_dwordx4 v[204:205], v[194:197], off
	v_cvt_pk_bf16_f32 v198, v22, v23
	v_cvt_pk_bf16_f32 v199, v24, v25
	v_cvt_pk_bf16_f32 v200, v18, v19
	v_cvt_pk_bf16_f32 v201, v20, v21
	v_add_u32_e32 v8, 0x54000, v138
	v_lshl_add_u64 v[144:145], v[8:9], 1, s[52:53]
	v_permlane16_swap_b32 v198, v200
	v_permlane16_swap_b32 v199, v201
	s_nop 1
	global_store_dwordx4 v[144:145], v[198:201], off
	v_cvt_pk_bf16_f32 v190, v14, v15
	v_cvt_pk_bf16_f32 v191, v16, v17
	v_cvt_pk_bf16_f32 v192, v10, v11
	v_cvt_pk_bf16_f32 v193, v12, v13
	v_add_u32_e32 v8, 0x54020, v138
	v_lshl_add_u64 v[202:203], v[8:9], 1, s[52:53]
	v_permlane16_swap_b32 v190, v192
	v_permlane16_swap_b32 v191, v193
	s_nop 1
	global_store_dwordx4 v[202:203], v[190:193], off
	s_branch .LBB0_606
.Lrk_slow:
	s_and_saveexec_b64 s[6:7], s[0:1]
	s_cbranch_execz .LBB0_647
	s_movk_i32 s0, 0xc3f
	v_cmp_lt_u32_e32 vcc, s0, v140
	s_and_saveexec_b64 s[0:1], vcc
	s_xor_b64 s[0:1], exec, s[0:1]
	s_cbranch_execz .LBB0_628
	s_cmpk_gt_u32 s13, 0xc7f
	s_mov_b64 s[10:11], -1
	s_cbranch_scc0 .LBB0_626
	s_movk_i32 s10, 0xd20
	v_cmp_gt_u32_e32 vcc, s10, v140
	v_mov_b32_e32 v139, 0
	v_mov_b32_e32 v138, 0
	s_and_saveexec_b64 s[10:11], vcc
	s_cbranch_execz .LBB0_625
	v_mul_f32_e32 v8, 0xbfb8aa3b, v134
	v_mul_f32_e32 v138, 0xbfb8aa3b, v135
	v_exp_f32_e32 v8, v8
	v_exp_f32_e32 v138, v138
	v_mul_f32_e32 v139, 0xbfb8aa3b, v137
	v_exp_f32_e32 v139, v139
	v_add_f32_e32 v8, 1.0, v8
	v_add_f32_e32 v138, 1.0, v138
	v_rcp_f32_e32 v8, v8
	v_rcp_f32_e32 v138, v138
	v_add_f32_e32 v139, 1.0, v139
	v_rcp_f32_e32 v139, v139
	v_cvt_pk_bf16_f32 v138, v8, v138
	v_mul_f32_e32 v8, 0xbfb8aa3b, v136
	v_exp_f32_e32 v8, v8
	s_nop 0
	v_add_f32_e32 v8, 1.0, v8
	v_rcp_f32_e32 v8, v8
	s_nop 0
	v_cvt_pk_bf16_f32 v139, v8, v139

;     ...
;           for (int mi = 0; mi < MI; mi++)
; #pragma unroll
;             for (int ni = 0; ni < 4; ni++)
;               acc[mi][ni] = __builtin_amdgcn_mfma_f32_16x16x32_bf16(bfr[ni], af[mi], acc[mi][ni], 0, 0, 0);
;     ...
;             } else if constexpr (EPI == EPI_HYB) {
;               if (col >= 1024 && col < 1536) {
;                 const unsigned bb = row / (unsigned)LP;
;                 const unsigned vb_ = ((bb * 8u + ((col - 1024) >> 6)) * 64u + (col & 63)) * (unsigned)LP + (row - bb * (unsigned)LP);
;                 e.b1[vb_] = f2bf(a[0]); e.b1[vb_ + LP] = f2bf(a[1]); e.b1[vb_ + 2 * LP] = f2bf(a[2]); e.b1[vb_ + 3 * LP] = f2bf(a[3]);
;               } else if (col < ZLD) {
;                 uint2 o; o.x = pack2(a[0], a[1]); o.y = pack2(a[2], a[3]);
;                 *(uint2*)(e.b0 + (row * (unsigned)ZLD + col)) = o;
;               } else if (col < ZLD + 16) {
;                 *(float4*)(e.f0 + (row * 16u + (col - ZLD))) = make_float4(a[0], a[1], a[2], a[3]);
;               }
.Lhy_last:
	v_mfma_f32_16x16x32_bf16 v[134:137], v[198:201], v[138:141], v[134:137]
	v_mfma_f32_16x16x32_bf16 v[130:133], v[202:205], v[138:141], v[130:133]
	v_mfma_f32_16x16x32_bf16 v[126:129], v[226:229], v[138:141], v[126:129]
	v_mfma_f32_16x16x32_bf16 v[122:125], v[230:233], v[138:141], v[122:125]
	v_mfma_f32_16x16x32_bf16 v[118:121], v[198:201], v[170:173], v[118:121]
	v_mfma_f32_16x16x32_bf16 v[114:117], v[202:205], v[170:173], v[114:117]
	v_mfma_f32_16x16x32_bf16 v[110:113], v[226:229], v[170:173], v[110:113]
	v_mfma_f32_16x16x32_bf16 v[106:109], v[230:233], v[170:173], v[106:109]
	v_mfma_f32_16x16x32_bf16 v[102:105], v[198:201], v[174:177], v[102:105]
	v_mfma_f32_16x16x32_bf16 v[98:101], v[202:205], v[174:177], v[98:101]
	v_mfma_f32_16x16x32_bf16 v[94:97], v[226:229], v[174:177], v[94:97]
	v_mfma_f32_16x16x32_bf16 v[90:93], v[230:233], v[174:177], v[90:93]
	v_mfma_f32_16x16x32_bf16 v[86:89], v[198:201], v[178:181], v[86:89]
	v_mfma_f32_16x16x32_bf16 v[82:85], v[202:205], v[178:181], v[82:85]
	v_mfma_f32_16x16x32_bf16 v[78:81], v[226:229], v[178:181], v[78:81]
	v_mfma_f32_16x16x32_bf16 v[74:77], v[230:233], v[178:181], v[74:77]
	v_mfma_f32_16x16x32_bf16 v[70:73], v[198:201], v[182:185], v[70:73]
	v_mfma_f32_16x16x32_bf16 v[66:69], v[202:205], v[182:185], v[66:69]
	v_mfma_f32_16x16x32_bf16 v[62:65], v[226:229], v[182:185], v[62:65]
	v_mfma_f32_16x16x32_bf16 v[58:61], v[230:233], v[182:185], v[58:61]
	v_mfma_f32_16x16x32_bf16 v[54:57], v[198:201], v[186:189], v[54:57]
	v_mfma_f32_16x16x32_bf16 v[50:53], v[202:205], v[186:189], v[50:53]
	v_mfma_f32_16x16x32_bf16 v[46:49], v[226:229], v[186:189], v[46:49]
	v_mfma_f32_16x16x32_bf16 v[42:45], v[230:233], v[186:189], v[42:45]
	v_mfma_f32_16x16x32_bf16 v[38:41], v[198:201], v[190:193], v[38:41]
	v_mfma_f32_16x16x32_bf16 v[34:37], v[202:205], v[190:193], v[34:37]
	v_mfma_f32_16x16x32_bf16 v[30:33], v[226:229], v[190:193], v[30:33]
	v_mfma_f32_16x16x32_bf16 v[26:29], v[230:233], v[190:193], v[26:29]
	v_mfma_f32_16x16x32_bf16 v[22:25], v[198:201], v[194:197], v[22:25]
	v_mfma_f32_16x16x32_bf16 v[18:21], v[202:205], v[194:197], v[18:21]
	v_mfma_f32_16x16x32_bf16 v[14:17], v[226:229], v[194:197], v[14:17]
	v_mfma_f32_16x16x32_bf16 v[10:13], v[230:233], v[194:197], v[10:13]
	s_cmpk_gt_u32 s9, 0xdff
	s_cbranch_scc1 .Lhy_slow
	s_and_b32 s4, s6, 0x1fffffc
	s_cmp_eq_u32 s4, 8
	s_cbranch_scc1 .Lhy_slow
;     ...
;             } else if constexpr (EPI == EPI_HYB) {
;               if (col >= 1024 && col < 1536) {
;                 const unsigned bb = row / (unsigned)LP;
;                 const unsigned vb_ = ((bb * 8u + ((col - 1024) >> 6)) * 64u + (col & 63)) * (unsigned)LP + (row - bb * (unsigned)LP);
;                 e.b1[vb_] = f2bf(a[0]); e.b1[vb_ + LP] = f2bf(a[1]); e.b1[vb_ + 2 * LP] = f2bf(a[2]); e.b1[vb_ + 3 * LP] = f2bf(a[3]);
;               } else if (col < ZLD) {
;                 uint2 o; o.x = pack2(a[0], a[1]); o.y = pack2(a[2], a[3]);
;                 *(uint2*)(e.b0 + (row * (unsigned)ZLD + col)) = o;
;               } else if (col < ZLD + 16) {
;                 *(float4*)(e.f0 + (row * 16u + (col - ZLD))) = make_float4(a[0], a[1], a[2], a[3]);
;               }
	v_add_u32_e32 v234, s7, v153
	v_or_b32_e32 v234, v234, v151
	s_movk_i32 s4, 0xe00
	v_mul_lo_u32 v235, v234, s4
	v_or_b32_e32 v236, s9, v155
	v_add_u32_e32 v235, v235, v236
	v_bfe_u32 v236, v2, 4, 1
	v_mul_u32_u24_e32 v236, 12, v236
	s_nop 0
	v_add_u32_e32 v235, v235, v236
	v_cvt_pk_bf16_f32 v170, v134, v135
	v_cvt_pk_bf16_f32 v171, v136, v137
	v_cvt_pk_bf16_f32 v172, v130, v131
	v_cvt_pk_bf16_f32 v173, v132, v133
	v_mov_b32_e32 v8, v235
	v_lshl_add_u64 v[186:187], v[8:9], 1, s[52:53]
	v_permlane16_swap_b32 v170, v172
	v_permlane16_swap_b32 v171, v173
	s_nop 1
	global_store_dwordx4 v[186:187], v[170:173], off
	v_cvt_pk_bf16_f32 v174, v126, v127
	v_cvt_pk_bf16_f32 v175, v128, v129
	v_cvt_pk_bf16_f32 v176, v122, v123
	v_cvt_pk_bf16_f32 v177, v124, v125
	v_add_u32_e32 v8, 0x20, v235
	v_lshl_add_u64 v[188:189], v[8:9], 1, s[52:53]
	v_permlane16_swap_b32 v174, v176
	v_permlane16_swap_b32 v175, v177
	s_nop 1
	global_store_dwordx4 v[188:189], v[174:177], off
	v_cvt_pk_bf16_f32 v178, v118, v119
	v_cvt_pk_bf16_f32 v179, v120, v121
	v_cvt_pk_bf16_f32 v180, v114, v115
	v_cvt_pk_bf16_f32 v181, v116, v117
	v_add_u32_e32 v8, 0xe000, v235
	v_lshl_add_u64 v[190:191], v[8:9], 1, s[52:53]
	v_permlane16_swap_b32 v178, v180
	v_permlane16_swap_b32 v179, v181
	s_nop 1
	global_store_dwordx4 v[190:191], v[178:181], off
	v_cvt_pk_bf16_f32 v182, v110, v111
	v_cvt_pk_bf16_f32 v183, v112, v113
	v_cvt_pk_bf16_f32 v184, v106, v107
	v_cvt_pk_bf16_f32 v185, v108, v109
	v_add_u32_e32 v8, 0xe020, v235
	v_lshl_add_u64 v[192:193], v[8:9], 1, s[52:53]
	v_permlane16_swap_b32 v182, v184
	v_permlane16_swap_b32 v183, v185
	s_nop 1
	global_store_dwordx4 v[192:193], v[182:185], off
	v_cvt_pk_bf16_f32 v170, v102, v103
	v_cvt_pk_bf16_f32 v171, v104, v105
	v_cvt_pk_bf16_f32 v172, v98, v99
	v_cvt_pk_bf16_f32 v173, v100, v101
	v_add_u32_e32 v8, 0x1c000, v235
	v_lshl_add_u64 v[186:187], v[8:9], 1, s[52:53]
	v_permlane16_swap_b32 v170, v172
	v_permlane16_swap_b32 v171, v173
	s_nop 1
	global_store_dwordx4 v[186:187], v[170:173], off
	v_cvt_pk_bf16_f32 v174, v94, v95
	v_cvt_pk_bf16_f32 v175, v96, v97
	v_cvt_pk_bf16_f32 v176, v90, v91
	v_cvt_pk_bf16_f32 v177, v92, v93
	v_add_u32_e32 v8, 0x1c020, v235
	v_lshl_add_u64 v[188:189], v[8:9], 1, s[52:53]
	v_permlane16_swap_b32 v174, v176
	v_permlane16_swap_b32 v175, v177
	s_nop 1
	global_store_dwordx4 v[188:189], v[174:177], off
	v_cvt_pk_bf16_f32 v178, v86, v87
	v_cvt_pk_bf16_f32 v179, v88, v89
	v_cvt_pk_bf16_f32 v180, v82, v83
	v_cvt_pk_bf16_f32 v181, v84, v85
	v_add_u32_e32 v8, 0x2a000, v235
	v_lshl_add_u64 v[190:191], v[8:9], 1, s[52:53]
	v_permlane16_swap_b32 v178, v180
	v_permlane16_swap_b32 v179, v181
	s_nop 1
	global_store_dwordx4 v[190:191], v[178:181], off
	v_cvt_pk_bf16_f32 v182, v78, v79
	v_cvt_pk_bf16_f32 v183, v80, v81
	v_cvt_pk_bf16_f32 v184, v74, v75
	v_cvt_pk_bf16_f32 v185, v76, v77
	v_add_u32_e32 v8, 0x2a020, v235
	v_lshl_add_u64 v[192:193], v[8:9], 1, s[52:53]
	v_permlane16_swap_b32 v182, v184
	v_permlane16_swap_b32 v183, v185
	s_nop 1
	global_store_dwordx4 v[192:193], v[182:185], off
	v_cvt_pk_bf16_f32 v170, v70, v71
	v_cvt_pk_bf16_f32 v171, v72, v73
	v_cvt_pk_bf16_f32 v172, v66, v67
	v_cvt_pk_bf16_f32 v173, v68, v69
	v_add_u32_e32 v8, 0x38000, v235
	v_lshl_add_u64 v[186:187], v[8:9], 1, s[52:53]
	v_permlane16_swap_b32 v170, v172
	v_permlane16_swap_b32 v171, v173
	s_nop 1
	global_store_dwordx4 v[186:187], v[170:173], off
	v_cvt_pk_bf16_f32 v174, v62, v63
	v_cvt_pk_bf16_f32 v175, v64, v65
	v_cvt_pk_bf16_f32 v176, v58, v59
	v_cvt_pk_bf16_f32 v177, v60, v61
	v_add_u32_e32 v8, 0x38020, v235
	v_lshl_add_u64 v[188:189], v[8:9], 1, s[52:53]
	v_permlane16_swap_b32 v174, v176
	v_permlane16_swap_b32 v175, v177
	s_nop 1
	global_store_dwordx4 v[188:189], v[174:177], off
	v_cvt_pk_bf16_f32 v178, v54, v55
	v_cvt_pk_bf16_f32 v179, v56, v57
	v_cvt_pk_bf16_f32 v180, v50, v51
	v_cvt_pk_bf16_f32 v181, v52, v53
	v_add_u32_e32 v8, 0x46000, v235
	v_lshl_add_u64 v[190:191], v[8:9], 1, s[52:53]
	v_permlane16_swap_b32 v178, v180
	v_permlane16_swap_b32 v179, v181
	s_nop 1
	global_store_dwordx4 v[190:191], v[178:181], off
	v_cvt_pk_bf16_f32 v182, v46, v47
	v_cvt_pk_bf16_f32 v183, v48, v49
	v_cvt_pk_bf16_f32 v184, v42, v43
	v_cvt_pk_bf16_f32 v185, v44, v45
	v_add_u32_e32 v8, 0x46020, v235
	v_lshl_add_u64 v[192:193], v[8:9], 1, s[52:53]
	v_permlane16_swap_b32 v182, v184
	v_permlane16_swap_b32 v183, v185
	s_nop 1
	global_store_dwordx4 v[192:193], v[182:185], off
	v_cvt_pk_bf16_f32 v170, v38, v39
	v_cvt_pk_bf16_f32 v171, v40, v41
	v_cvt_pk_bf16_f32 v172, v34, v35
	v_cvt_pk_bf16_f32 v173, v36, v37
	v_add_u32_e32 v8, 0x54000, v235
	v_lshl_add_u64 v[186:187], v[8:9], 1, s[52:53]
	v_permlane16_swap_b32 v170, v172
	v_permlane16_swap_b32 v171, v173
	s_nop 1
	global_store_dwordx4 v[186:187], v[170:173], off
	v_cvt_pk_bf16_f32 v174, v30, v31
	v_cvt_pk_bf16_f32 v175, v32, v33
	v_cvt_pk_bf16_f32 v176, v26, v27
	v_cvt_pk_bf16_f32 v177, v28, v29
	v_add_u32_e32 v8, 0x54020, v235
	v_lshl_add_u64 v[188:189], v[8:9], 1, s[52:53]
	v_permlane16_swap_b32 v174, v176
	v_permlane16_swap_b32 v175, v177
	s_nop 1
	global_store_dwordx4 v[188:189], v[174:177], off
	v_cvt_pk_bf16_f32 v178, v22, v23
	v_cvt_pk_bf16_f32 v179, v24, v25
	v_cvt_pk_bf16_f32 v180, v18, v19
	v_cvt_pk_bf16_f32 v181, v20, v21
	v_add_u32_e32 v8, 0x62000, v235
	v_lshl_add_u64 v[190:191], v[8:9], 1, s[52:53]
	v_permlane16_swap_b32 v178, v180
	v_permlane16_swap_b32 v179, v181
	s_nop 1
	global_store_dwordx4 v[190:191], v[178:181], off
	v_cvt_pk_bf16_f32 v182, v14, v15
	v_cvt_pk_bf16_f32 v183, v16, v17
	v_cvt_pk_bf16_f32 v184, v10, v11
	v_cvt_pk_bf16_f32 v185, v12, v13
	v_add_u32_e32 v8, 0x62020, v235
	v_lshl_add_u64 v[192:193], v[8:9], 1, s[52:53]
	v_permlane16_swap_b32 v182, v184
	v_permlane16_swap_b32 v183, v185
	s_nop 1
	global_store_dwordx4 v[192:193], v[182:185], off
	s_branch .LBB0_2183
.Lhy_slow:
	s_and_b32 s4, s6, 0x1fffffc
	v_add_u32_e32 v139, s7, v153
	s_cmp_lg_u32 s4, 8
	v_or_b32_e32 v138, v139, v151
	s_cselect_b64 s[4:5], -1, 0
	s_movk_i32 s6, 0xe00
	v_lshl_add_u32 v147, v138, 4, v223
	v_mul_lo_u32 v146, v138, s6
	v_or_b32_e32 v140, s9, v155
	s_mov_b64 s[6:7], -1
	s_and_b64 vcc, exec, s[4:5]
	s_cbranch_vccz .LBB0_2204
	s_cmpk_gt_u32 s9, 0xdff
	s_cbranch_scc0 .LBB0_2201
	s_movk_i32 s6, 0xe10
	v_cmp_gt_u32_e32 vcc, s6, v140
	s_and_saveexec_b64 s[6:7], vcc
	s_cbranch_execz .LBB0_2200
	v_readlane_b32 s10, v246, 11
	v_add_u32_e32 v8, v147, v140
	v_readlane_b32 s11, v246, 12
	s_nop 1
	v_lshl_add_u64 v[148:149], v[8:9], 2, s[10:11]
	global_store_dwordx4 v[148:149], v[134:137], off
